# GEMM K-loops: back-edge rotation (next-tile LDS address ALU moved before the loop barrier) + first two LDS-DMA loads issued in the post-barrier LDS-latency bubble
# speedup vs baseline: 1.0057x; 1.0057x over previous
; #define WAIT_V0() asm volatile("s_waitcnt vmcnt(0)" ::: "memory")
;     ...
;   GLDS_STAGE(0, 0); WAIT_V0(); __syncthreads();
;   for (int t = 0; t < nt; ++t) {
;     const int cur = t & 1;
;     if (t + 1 < nt) GLDS_STAGE(cur ^ 1, t + 1);
; #pragma unroll
;     for (int ks = 0; ks < KS; ++ks) {
;       bf16x8 At[8], Bf[NB];
; #pragma unroll
;       for (int m = 0; m < 8; ++m) At[m] = *(const bf16x8*)(SA(cur) + lds_byte<KS>(wr * 128 + m * 16 + fr, ks * 32 + fq * 8));
; #pragma unroll
;       for (int n = 0; n < NB; ++n) Bf[n] = *(const bf16x8*)(SB(cur) + lds_byte<KS>(wc * (16 * NB) + n * 16 + fr, ks * 32 + fq * 8));
; #pragma unroll
;       for (int m = 0; m < 8; ++m)
; #pragma unroll
;         for (int n = 0; n < NB; ++n) acc[m][n] = __builtin_amdgcn_mfma_f32_16x16x32_bf16(Bf[n], At[m], acc[m][n], 0, 0, 0);
.LBB0_235:
	s_or_b64 exec, exec, s[20:21]
	s_waitcnt vmcnt(0)
	s_add_u32 s74, s74, 0x80
	s_addc_u32 s75, s75, 0
	s_add_i32 s22, s22, 1
	s_and_b32 s23, s22, 1
	s_xor_b32 s54, s23, 1
	s_mul_i32 s54, s54, 0x10800
	s_mul_i32 s23, s23, 0x10800
	v_or_b32_e32 v128, s23, v229
	v_add_u32_e32 v223, v128, v191
	v_add_u32_e32 v227, v128, v190
	v_readfirstlane_b32 s100, v180
	s_add_i32 s100, s100, s54
	s_cmpk_lg_i32 s74, 0x780
	s_waitcnt vmcnt(0)
	s_barrier
	s_cbranch_scc0 .LBB0_242
.Lgk_inproj_body:
	ds_read_b128 v[146:149], v223 offset:34816
	ds_read_b128 v[208:211], v227
	ds_read_b128 v[150:153], v223 offset:36864
	ds_read_b128 v[154:157], v223 offset:38912
	ds_read_b128 v[158:161], v223 offset:40960
	ds_read_b128 v[212:215], v227 offset:2048
	s_mov_b32 m0, s100
	v_lshl_add_u64 v[220:221], v[162:163], 0, s[74:75]
	global_load_lds_dwordx4 v[220:221], off
	s_add_i32 m0, s100, 0x8800
	v_lshl_add_u64 v[220:221], v[170:171], 0, s[74:75]
	global_load_lds_dwordx4 v[220:221], off
	s_waitcnt lgkmcnt(1)
	v_mfma_f32_16x16x32_bf16 v[142:145], v[146:149], v[208:211], v[142:145]
	v_mfma_f32_16x16x32_bf16 v[138:141], v[150:153], v[208:211], v[138:141]
	v_mfma_f32_16x16x32_bf16 v[134:137], v[154:157], v[208:211], v[134:137]
	v_mfma_f32_16x16x32_bf16 v[130:133], v[158:161], v[208:211], v[130:133]
	ds_read_b128 v[216:219], v227 offset:4096
	s_add_i32 m0, s100, 0x2000
	v_lshl_add_u64 v[220:221], v[164:165], 0, s[74:75]
	global_load_lds_dwordx4 v[220:221], off
	s_waitcnt lgkmcnt(1)
	v_mfma_f32_16x16x32_bf16 v[124:127], v[146:149], v[212:215], v[124:127]
	v_mfma_f32_16x16x32_bf16 v[120:123], v[150:153], v[212:215], v[120:123]
	v_mfma_f32_16x16x32_bf16 v[116:119], v[154:157], v[212:215], v[116:119]
	v_mfma_f32_16x16x32_bf16 v[92:95], v[158:161], v[212:215], v[92:95]
	ds_read_b128 v[208:211], v227 offset:6144
	s_add_i32 m0, s100, 0xa800
	v_lshl_add_u64 v[220:221], v[172:173], 0, s[74:75]
	global_load_lds_dwordx4 v[220:221], off
	s_waitcnt lgkmcnt(1)
	v_mfma_f32_16x16x32_bf16 v[60:63], v[146:149], v[216:219], v[60:63]
	v_mfma_f32_16x16x32_bf16 v[40:43], v[150:153], v[216:219], v[40:43]
	v_mfma_f32_16x16x32_bf16 v[36:39], v[154:157], v[216:219], v[36:39]
	v_mfma_f32_16x16x32_bf16 v[32:35], v[158:161], v[216:219], v[32:35]
	ds_read_b128 v[212:215], v227 offset:8192
	s_add_i32 m0, s100, 0x4000
	v_lshl_add_u64 v[220:221], v[166:167], 0, s[74:75]
	global_load_lds_dwordx4 v[220:221], off
	s_waitcnt lgkmcnt(1)
	v_mfma_f32_16x16x32_bf16 v[28:31], v[146:149], v[208:211], v[28:31]
	v_mfma_f32_16x16x32_bf16 v[24:27], v[150:153], v[208:211], v[24:27]
	v_mfma_f32_16x16x32_bf16 v[20:23], v[154:157], v[208:211], v[20:23]
	v_mfma_f32_16x16x32_bf16 v[16:19], v[158:161], v[208:211], v[16:19]
	ds_read_b128 v[216:219], v227 offset:10240
	s_add_i32 m0, s100, 0xc800
	v_lshl_add_u64 v[220:221], v[174:175], 0, s[74:75]
	global_load_lds_dwordx4 v[220:221], off
	s_waitcnt lgkmcnt(1)
	v_mfma_f32_16x16x32_bf16 v[84:87], v[146:149], v[212:215], v[84:87]
	v_mfma_f32_16x16x32_bf16 v[100:103], v[150:153], v[212:215], v[100:103]
	v_mfma_f32_16x16x32_bf16 v[108:111], v[154:157], v[212:215], v[108:111]
	v_mfma_f32_16x16x32_bf16 v[48:51], v[158:161], v[212:215], v[48:51]
	ds_read_b128 v[192:195], v223 offset:35840
	ds_read_b128 v[208:211], v227 offset:12288
	s_add_i32 m0, s100, 0x6000
	v_lshl_add_u64 v[220:221], v[168:169], 0, s[74:75]
	global_load_lds_dwordx4 v[220:221], off
	s_waitcnt lgkmcnt(2)
	v_mfma_f32_16x16x32_bf16 v[44:47], v[146:149], v[216:219], v[44:47]
	v_mfma_f32_16x16x32_bf16 v[64:67], v[150:153], v[216:219], v[64:67]
	v_mfma_f32_16x16x32_bf16 v[72:75], v[154:157], v[216:219], v[72:75]
	v_mfma_f32_16x16x32_bf16 v[76:79], v[158:161], v[216:219], v[76:79]
	ds_read_b128 v[196:199], v223 offset:37888
	ds_read_b128 v[212:215], v227 offset:14336
	s_add_i32 m0, s100, 0xe800
	v_lshl_add_u64 v[220:221], v[176:177], 0, s[74:75]
	global_load_lds_dwordx4 v[220:221], off
	s_waitcnt lgkmcnt(2)
	v_mfma_f32_16x16x32_bf16 v[96:99], v[146:149], v[208:211], v[96:99]
	v_mfma_f32_16x16x32_bf16 v[104:107], v[150:153], v[208:211], v[104:107]
	v_mfma_f32_16x16x32_bf16 v[112:115], v[154:157], v[208:211], v[112:115]
	v_mfma_f32_16x16x32_bf16 v[56:59], v[158:161], v[208:211], v[56:59]
	ds_read_b128 v[200:203], v223 offset:39936
	ds_read_b128 v[216:219], v227 offset:1024
	s_and_saveexec_b64 s[20:21], s[8:9]
	s_cbranch_execz .Lgk_inproj_xl
	v_readfirstlane_b32 s101, v189
	s_add_i32 s101, s101, s54
	s_add_i32 m0, s101, 0x8000
	v_lshl_add_u64 v[220:221], v[178:179], 0, s[74:75]
	global_load_lds_dwordx4 v[220:221], off
; #define WAIT_V0() asm volatile("s_waitcnt vmcnt(0)" ::: "memory")
; #define SBAR() __builtin_amdgcn_sched_barrier(0)
;     ...
;     for (int ks = 0; ks < KS; ++ks) {
;       bf16x8 At[8], Bf[NB];
; #pragma unroll
;       for (int m = 0; m < 8; ++m) At[m] = *(const bf16x8*)(SA(cur) + lds_byte<KS>(wr * 128 + m * 16 + fr, ks * 32 + fq * 8));
; #pragma unroll
;       for (int n = 0; n < NB; ++n) Bf[n] = *(const bf16x8*)(SB(cur) + lds_byte<KS>(wc * (16 * NB) + n * 16 + fr, ks * 32 + fq * 8));
; #pragma unroll
;       for (int m = 0; m < 8; ++m)
; #pragma unroll
;         for (int n = 0; n < NB; ++n) acc[m][n] = __builtin_amdgcn_mfma_f32_16x16x32_bf16(Bf[n], At[m], acc[m][n], 0, 0, 0);
;       if (xmma) {
;         const bf16x8 Ax = *(const bf16x8*)(SA(cur) + lds_byte<KS>(256 + fr, ks * 32 + fq * 8));
; #pragma unroll
;         for (int n = 0; n < NB; ++n) accx[n] = __builtin_amdgcn_mfma_f32_16x16x32_bf16(Bf[n], Ax, accx[n], 0, 0, 0);
;       }
;       SBAR();
;     }
;     WAIT_V0(); __syncthreads();
.Lgk_inproj_xl:
	s_or_b64 exec, exec, s[20:21]
	s_waitcnt lgkmcnt(2)
	v_mfma_f32_16x16x32_bf16 v[52:55], v[146:149], v[212:215], v[52:55]
	v_mfma_f32_16x16x32_bf16 v[68:71], v[150:153], v[212:215], v[68:71]
	v_mfma_f32_16x16x32_bf16 v[80:83], v[154:157], v[212:215], v[80:83]
	v_mfma_f32_16x16x32_bf16 v[88:91], v[158:161], v[212:215], v[88:91]
	ds_read_b128 v[204:207], v223 offset:41984
	ds_read_b128 v[208:211], v227 offset:3072
	s_waitcnt lgkmcnt(1)
	v_mfma_f32_16x16x32_bf16 v[142:145], v[192:195], v[216:219], v[142:145]
	v_mfma_f32_16x16x32_bf16 v[138:141], v[196:199], v[216:219], v[138:141]
	v_mfma_f32_16x16x32_bf16 v[134:137], v[200:203], v[216:219], v[134:137]
	v_mfma_f32_16x16x32_bf16 v[130:133], v[204:207], v[216:219], v[130:133]
	ds_read_b128 v[212:215], v227 offset:5120
	s_waitcnt lgkmcnt(1)
	v_mfma_f32_16x16x32_bf16 v[124:127], v[192:195], v[208:211], v[124:127]
	v_mfma_f32_16x16x32_bf16 v[120:123], v[196:199], v[208:211], v[120:123]
	v_mfma_f32_16x16x32_bf16 v[116:119], v[200:203], v[208:211], v[116:119]
	v_mfma_f32_16x16x32_bf16 v[92:95], v[204:207], v[208:211], v[92:95]
	ds_read_b128 v[216:219], v227 offset:7168
	s_waitcnt lgkmcnt(1)
	v_mfma_f32_16x16x32_bf16 v[60:63], v[192:195], v[212:215], v[60:63]
	v_mfma_f32_16x16x32_bf16 v[40:43], v[196:199], v[212:215], v[40:43]
	v_mfma_f32_16x16x32_bf16 v[36:39], v[200:203], v[212:215], v[36:39]
	v_mfma_f32_16x16x32_bf16 v[32:35], v[204:207], v[212:215], v[32:35]
	ds_read_b128 v[208:211], v227 offset:9216
	s_waitcnt lgkmcnt(1)
	v_mfma_f32_16x16x32_bf16 v[28:31], v[192:195], v[216:219], v[28:31]
	v_mfma_f32_16x16x32_bf16 v[24:27], v[196:199], v[216:219], v[24:27]
	v_mfma_f32_16x16x32_bf16 v[20:23], v[200:203], v[216:219], v[20:23]
	v_mfma_f32_16x16x32_bf16 v[16:19], v[204:207], v[216:219], v[16:19]
	ds_read_b128 v[212:215], v227 offset:11264
	s_waitcnt lgkmcnt(1)
	v_mfma_f32_16x16x32_bf16 v[84:87], v[192:195], v[208:211], v[84:87]
	v_mfma_f32_16x16x32_bf16 v[100:103], v[196:199], v[208:211], v[100:103]
	v_mfma_f32_16x16x32_bf16 v[108:111], v[200:203], v[208:211], v[108:111]
	v_mfma_f32_16x16x32_bf16 v[48:51], v[204:207], v[208:211], v[48:51]
	ds_read_b128 v[216:219], v227 offset:13312
	s_waitcnt lgkmcnt(1)
	v_mfma_f32_16x16x32_bf16 v[44:47], v[192:195], v[212:215], v[44:47]
	v_mfma_f32_16x16x32_bf16 v[64:67], v[196:199], v[212:215], v[64:67]
	v_mfma_f32_16x16x32_bf16 v[72:75], v[200:203], v[212:215], v[72:75]
	v_mfma_f32_16x16x32_bf16 v[76:79], v[204:207], v[212:215], v[76:79]
	ds_read_b128 v[208:211], v227 offset:15360
	s_waitcnt lgkmcnt(1)
	v_mfma_f32_16x16x32_bf16 v[96:99], v[192:195], v[216:219], v[96:99]
	v_mfma_f32_16x16x32_bf16 v[104:107], v[196:199], v[216:219], v[104:107]
	v_mfma_f32_16x16x32_bf16 v[112:115], v[200:203], v[216:219], v[112:115]
	v_mfma_f32_16x16x32_bf16 v[56:59], v[204:207], v[216:219], v[56:59]
	s_waitcnt lgkmcnt(0)
	v_mfma_f32_16x16x32_bf16 v[52:55], v[192:195], v[208:211], v[52:55]
	v_mfma_f32_16x16x32_bf16 v[68:71], v[196:199], v[208:211], v[68:71]
	v_mfma_f32_16x16x32_bf16 v[80:83], v[200:203], v[208:211], v[80:83]
	v_mfma_f32_16x16x32_bf16 v[88:91], v[204:207], v[208:211], v[88:91]
	s_and_saveexec_b64 s[20:21], s[6:7]
	s_cbranch_execz .LBB0_235
	v_add_u32_e32 v230, s23, v229
	ds_read_b128 v[212:215], v230 offset:32768
	ds_read_b128 v[216:219], v230 offset:33792
	s_waitcnt lgkmcnt(1)
	v_mfma_f32_16x16x32_bf16 v[12:15], v[146:149], v[212:215], v[12:15]
	v_mfma_f32_16x16x32_bf16 v[4:7], v[150:153], v[212:215], v[4:7]
	v_mfma_f32_16x16x32_bf16 v[8:11], v[154:157], v[212:215], v[8:11]
	v_mfma_f32_16x16x32_bf16 v[0:3], v[158:161], v[212:215], v[0:3]
	s_waitcnt lgkmcnt(0)
	v_mfma_f32_16x16x32_bf16 v[12:15], v[192:195], v[216:219], v[12:15]
	v_mfma_f32_16x16x32_bf16 v[4:7], v[196:199], v[216:219], v[4:7]
	v_mfma_f32_16x16x32_bf16 v[8:11], v[200:203], v[216:219], v[8:11]
	v_mfma_f32_16x16x32_bf16 v[0:3], v[204:207], v[216:219], v[0:3]
	s_branch .LBB0_235
.LBB0_236:
	s_and_b32 s23, s22, 1
	s_xor_b32 s54, s23, 1
	s_mul_i32 s54, s54, 0x10800
	s_mul_i32 s23, s23, 0x10800
	v_or_b32_e32 v128, s23, v229
	v_add_u32_e32 v223, v128, v191
	v_add_u32_e32 v227, v128, v190
	v_readfirstlane_b32 s100, v180
	s_add_i32 s100, s100, s54
	s_branch .Lgk_inproj_body

; #define WAIT_V0() asm volatile("s_waitcnt vmcnt(0)" ::: "memory")
; #define SBAR() __builtin_amdgcn_sched_barrier(0)
;     ...
;   for (int t = 0; t < nt; ++t) {
;     const int cur = t & 1;
;     if (t + 1 < nt) GLDS_STAGE(cur ^ 1, t + 1);
; #pragma unroll
;     for (int ks = 0; ks < KS; ++ks) {
;       bf16x8 At[8], Bf[NB];
; #pragma unroll
;       for (int m = 0; m < 8; ++m) At[m] = *(const bf16x8*)(SA(cur) + lds_byte<KS>(wr * 128 + m * 16 + fr, ks * 32 + fq * 8));
; #pragma unroll
;       for (int n = 0; n < NB; ++n) Bf[n] = *(const bf16x8*)(SB(cur) + lds_byte<KS>(wc * (16 * NB) + n * 16 + fr, ks * 32 + fq * 8));
; #pragma unroll
;       for (int m = 0; m < 8; ++m)
; #pragma unroll
;         for (int n = 0; n < NB; ++n) acc[m][n] = __builtin_amdgcn_mfma_f32_16x16x32_bf16(Bf[n], At[m], acc[m][n], 0, 0, 0);
;       if (xmma) {
;         const bf16x8 Ax = *(const bf16x8*)(SA(cur) + lds_byte<KS>(256 + fr, ks * 32 + fq * 8));
; #pragma unroll
;         for (int n = 0; n < NB; ++n) accx[n] = __builtin_amdgcn_mfma_f32_16x16x32_bf16(Bf[n], Ax, accx[n], 0, 0, 0);
;       }
;       SBAR();
;     }
;     WAIT_V0(); __syncthreads();
.LBB0_278:
	s_or_b64 exec, exec, s[20:21]
	s_add_i32 s23, s23, 1
	s_waitcnt vmcnt(0)
	s_add_u32 s66, s66, 0x80
	s_addc_u32 s67, s67, 0
	s_and_b32 s75, s23, 1
	s_xor_b32 s76, s75, 1
	s_mul_i32 s76, s76, 0x10800
	s_mul_i32 s75, s75, 0x10800
	v_or_b32_e32 v128, s75, v184
	v_add_u32_e32 v226, v128, v195
	v_add_u32_e32 v227, v128, v194
	v_readfirstlane_b32 s100, v183
	s_add_i32 s100, s100, s76
	s_cmp_lg_u32 s22, s23
	s_waitcnt vmcnt(0)
	s_barrier
	s_cbranch_scc0 .LBB0_285
.Lgk_upproj_body:
	ds_read_b128 v[146:149], v226 offset:34816
	ds_read_b128 v[212:215], v227
	ds_read_b128 v[150:153], v226 offset:36864
	ds_read_b128 v[154:157], v226 offset:38912
	ds_read_b128 v[158:161], v226 offset:40960
	ds_read_b128 v[216:219], v227 offset:2048
	s_mov_b32 m0, s100
	v_lshl_add_u64 v[224:225], v[162:163], 0, s[66:67]
	global_load_lds_dwordx4 v[224:225], off
	s_add_i32 m0, s100, 0x8800
	v_lshl_add_u64 v[224:225], v[172:173], 0, s[66:67]
	global_load_lds_dwordx4 v[224:225], off
	s_waitcnt lgkmcnt(1)
	v_mfma_f32_16x16x32_bf16 v[142:145], v[146:149], v[212:215], v[142:145]
	v_mfma_f32_16x16x32_bf16 v[138:141], v[150:153], v[212:215], v[138:141]
	v_mfma_f32_16x16x32_bf16 v[134:137], v[154:157], v[212:215], v[134:137]
	v_mfma_f32_16x16x32_bf16 v[130:133], v[158:161], v[212:215], v[130:133]
	ds_read_b128 v[220:223], v227 offset:4096
	s_add_i32 m0, s100, 0x2000
	v_lshl_add_u64 v[224:225], v[164:165], 0, s[66:67]
	global_load_lds_dwordx4 v[224:225], off
	s_waitcnt lgkmcnt(1)
	v_mfma_f32_16x16x32_bf16 v[124:127], v[146:149], v[216:219], v[124:127]
	v_mfma_f32_16x16x32_bf16 v[120:123], v[150:153], v[216:219], v[120:123]
	v_mfma_f32_16x16x32_bf16 v[116:119], v[154:157], v[216:219], v[116:119]
	v_mfma_f32_16x16x32_bf16 v[112:115], v[158:161], v[216:219], v[112:115]
	ds_read_b128 v[212:215], v227 offset:6144
	s_add_i32 m0, s100, 0xa800
	v_lshl_add_u64 v[224:225], v[174:175], 0, s[66:67]
	global_load_lds_dwordx4 v[224:225], off
	s_waitcnt lgkmcnt(1)
	v_mfma_f32_16x16x32_bf16 v[108:111], v[146:149], v[220:223], v[108:111]
	v_mfma_f32_16x16x32_bf16 v[104:107], v[150:153], v[220:223], v[104:107]
	v_mfma_f32_16x16x32_bf16 v[100:103], v[154:157], v[220:223], v[100:103]
	v_mfma_f32_16x16x32_bf16 v[96:99], v[158:161], v[220:223], v[96:99]
	ds_read_b128 v[216:219], v227 offset:8192
	s_add_i32 m0, s100, 0x4000
	v_lshl_add_u64 v[224:225], v[168:169], 0, s[66:67]
	global_load_lds_dwordx4 v[224:225], off
	s_waitcnt lgkmcnt(1)
	v_mfma_f32_16x16x32_bf16 v[92:95], v[146:149], v[212:215], v[92:95]
	v_mfma_f32_16x16x32_bf16 v[88:91], v[150:153], v[212:215], v[88:91]
	v_mfma_f32_16x16x32_bf16 v[84:87], v[154:157], v[212:215], v[84:87]
	v_mfma_f32_16x16x32_bf16 v[80:83], v[158:161], v[212:215], v[80:83]
	ds_read_b128 v[220:223], v227 offset:10240
	s_add_i32 m0, s100, 0xc800
	v_lshl_add_u64 v[224:225], v[176:177], 0, s[66:67]
	global_load_lds_dwordx4 v[224:225], off
	s_waitcnt lgkmcnt(1)
	v_mfma_f32_16x16x32_bf16 v[76:79], v[146:149], v[216:219], v[76:79]
	v_mfma_f32_16x16x32_bf16 v[72:75], v[150:153], v[216:219], v[72:75]
	v_mfma_f32_16x16x32_bf16 v[68:71], v[154:157], v[216:219], v[68:71]
	v_mfma_f32_16x16x32_bf16 v[64:67], v[158:161], v[216:219], v[64:67]
	ds_read_b128 v[196:199], v226 offset:35840
	ds_read_b128 v[212:215], v227 offset:12288
	s_add_i32 m0, s100, 0x6000
	v_lshl_add_u64 v[224:225], v[170:171], 0, s[66:67]
	global_load_lds_dwordx4 v[224:225], off
	s_waitcnt lgkmcnt(2)
	v_mfma_f32_16x16x32_bf16 v[60:63], v[146:149], v[220:223], v[60:63]
	v_mfma_f32_16x16x32_bf16 v[56:59], v[150:153], v[220:223], v[56:59]
	v_mfma_f32_16x16x32_bf16 v[52:55], v[154:157], v[220:223], v[52:55]
	v_mfma_f32_16x16x32_bf16 v[48:51], v[158:161], v[220:223], v[48:51]
	ds_read_b128 v[200:203], v226 offset:37888
	ds_read_b128 v[216:219], v227 offset:14336
	s_add_i32 m0, s100, 0xe800
	v_lshl_add_u64 v[224:225], v[178:179], 0, s[66:67]
	global_load_lds_dwordx4 v[224:225], off
	s_waitcnt lgkmcnt(2)
	v_mfma_f32_16x16x32_bf16 v[44:47], v[146:149], v[212:215], v[44:47]
	v_mfma_f32_16x16x32_bf16 v[40:43], v[150:153], v[212:215], v[40:43]
	v_mfma_f32_16x16x32_bf16 v[36:39], v[154:157], v[212:215], v[36:39]
	v_mfma_f32_16x16x32_bf16 v[32:35], v[158:161], v[212:215], v[32:35]
	ds_read_b128 v[204:207], v226 offset:39936
	ds_read_b128 v[220:223], v227 offset:1024
	s_and_saveexec_b64 s[20:21], s[64:65]
	s_cbranch_execz .Lgk_upproj_xl
	v_readfirstlane_b32 s101, v193
	s_add_i32 s101, s101, s76
	s_add_i32 m0, s101, 0x8000
	v_lshl_add_u64 v[224:225], v[180:181], 0, s[66:67]
	global_load_lds_dwordx4 v[224:225], off
; #define WAIT_V0() asm volatile("s_waitcnt vmcnt(0)" ::: "memory")
; #define SBAR() __builtin_amdgcn_sched_barrier(0)
;     ...
;   for (int t = 0; t < nt; ++t) {
;     const int cur = t & 1;
;     if (t + 1 < nt) GLDS_STAGE(cur ^ 1, t + 1);
; #pragma unroll
;     for (int ks = 0; ks < KS; ++ks) {
;       bf16x8 At[8], Bf[NB];
; #pragma unroll
;       for (int m = 0; m < 8; ++m) At[m] = *(const bf16x8*)(SA(cur) + lds_byte<KS>(wr * 128 + m * 16 + fr, ks * 32 + fq * 8));
; #pragma unroll
;       for (int n = 0; n < NB; ++n) Bf[n] = *(const bf16x8*)(SB(cur) + lds_byte<KS>(wc * (16 * NB) + n * 16 + fr, ks * 32 + fq * 8));
; #pragma unroll
;       for (int m = 0; m < 8; ++m)
; #pragma unroll
;         for (int n = 0; n < NB; ++n) acc[m][n] = __builtin_amdgcn_mfma_f32_16x16x32_bf16(Bf[n], At[m], acc[m][n], 0, 0, 0);
;       if (xmma) {
;         const bf16x8 Ax = *(const bf16x8*)(SA(cur) + lds_byte<KS>(256 + fr, ks * 32 + fq * 8));
; #pragma unroll
;         for (int n = 0; n < NB; ++n) accx[n] = __builtin_amdgcn_mfma_f32_16x16x32_bf16(Bf[n], Ax, accx[n], 0, 0, 0);
;       }
;       SBAR();
;     }
;     WAIT_V0(); __syncthreads();
.Lgk_upproj_xl:
	s_or_b64 exec, exec, s[20:21]
	s_waitcnt lgkmcnt(2)
	v_mfma_f32_16x16x32_bf16 v[28:31], v[146:149], v[216:219], v[28:31]
	v_mfma_f32_16x16x32_bf16 v[24:27], v[150:153], v[216:219], v[24:27]
	v_mfma_f32_16x16x32_bf16 v[20:23], v[154:157], v[216:219], v[20:23]
	v_mfma_f32_16x16x32_bf16 v[16:19], v[158:161], v[216:219], v[16:19]
	ds_read_b128 v[208:211], v226 offset:41984
	ds_read_b128 v[212:215], v227 offset:3072
	s_waitcnt lgkmcnt(1)
	v_mfma_f32_16x16x32_bf16 v[142:145], v[196:199], v[220:223], v[142:145]
	v_mfma_f32_16x16x32_bf16 v[138:141], v[200:203], v[220:223], v[138:141]
	v_mfma_f32_16x16x32_bf16 v[134:137], v[204:207], v[220:223], v[134:137]
	v_mfma_f32_16x16x32_bf16 v[130:133], v[208:211], v[220:223], v[130:133]
	ds_read_b128 v[216:219], v227 offset:5120
	s_waitcnt lgkmcnt(1)
	v_mfma_f32_16x16x32_bf16 v[124:127], v[196:199], v[212:215], v[124:127]
	v_mfma_f32_16x16x32_bf16 v[120:123], v[200:203], v[212:215], v[120:123]
	v_mfma_f32_16x16x32_bf16 v[116:119], v[204:207], v[212:215], v[116:119]
	v_mfma_f32_16x16x32_bf16 v[112:115], v[208:211], v[212:215], v[112:115]
	ds_read_b128 v[220:223], v227 offset:7168
	s_waitcnt lgkmcnt(1)
	v_mfma_f32_16x16x32_bf16 v[108:111], v[196:199], v[216:219], v[108:111]
	v_mfma_f32_16x16x32_bf16 v[104:107], v[200:203], v[216:219], v[104:107]
	v_mfma_f32_16x16x32_bf16 v[100:103], v[204:207], v[216:219], v[100:103]
	v_mfma_f32_16x16x32_bf16 v[96:99], v[208:211], v[216:219], v[96:99]
	ds_read_b128 v[212:215], v227 offset:9216
	s_waitcnt lgkmcnt(1)
	v_mfma_f32_16x16x32_bf16 v[92:95], v[196:199], v[220:223], v[92:95]
	v_mfma_f32_16x16x32_bf16 v[88:91], v[200:203], v[220:223], v[88:91]
	v_mfma_f32_16x16x32_bf16 v[84:87], v[204:207], v[220:223], v[84:87]
	v_mfma_f32_16x16x32_bf16 v[80:83], v[208:211], v[220:223], v[80:83]
	ds_read_b128 v[216:219], v227 offset:11264
	s_waitcnt lgkmcnt(1)
	v_mfma_f32_16x16x32_bf16 v[76:79], v[196:199], v[212:215], v[76:79]
	v_mfma_f32_16x16x32_bf16 v[72:75], v[200:203], v[212:215], v[72:75]
	v_mfma_f32_16x16x32_bf16 v[68:71], v[204:207], v[212:215], v[68:71]
	v_mfma_f32_16x16x32_bf16 v[64:67], v[208:211], v[212:215], v[64:67]
	ds_read_b128 v[220:223], v227 offset:13312
	s_waitcnt lgkmcnt(1)
	v_mfma_f32_16x16x32_bf16 v[60:63], v[196:199], v[216:219], v[60:63]
	v_mfma_f32_16x16x32_bf16 v[56:59], v[200:203], v[216:219], v[56:59]
	v_mfma_f32_16x16x32_bf16 v[52:55], v[204:207], v[216:219], v[52:55]
	v_mfma_f32_16x16x32_bf16 v[48:51], v[208:211], v[216:219], v[48:51]
	ds_read_b128 v[212:215], v227 offset:15360
	s_waitcnt lgkmcnt(1)
	v_mfma_f32_16x16x32_bf16 v[44:47], v[196:199], v[220:223], v[44:47]
	v_mfma_f32_16x16x32_bf16 v[40:43], v[200:203], v[220:223], v[40:43]
	v_mfma_f32_16x16x32_bf16 v[36:39], v[204:207], v[220:223], v[36:39]
	v_mfma_f32_16x16x32_bf16 v[32:35], v[208:211], v[220:223], v[32:35]
	s_waitcnt lgkmcnt(0)
	v_mfma_f32_16x16x32_bf16 v[28:31], v[196:199], v[212:215], v[28:31]
	v_mfma_f32_16x16x32_bf16 v[24:27], v[200:203], v[212:215], v[24:27]
	v_mfma_f32_16x16x32_bf16 v[20:23], v[204:207], v[212:215], v[20:23]
	v_mfma_f32_16x16x32_bf16 v[16:19], v[208:211], v[212:215], v[16:19]
	s_and_saveexec_b64 s[20:21], s[18:19]
	s_cbranch_execz .LBB0_278
	v_add_u32_e32 v228, s75, v184
	ds_read_b128 v[216:219], v228 offset:32768
	ds_read_b128 v[220:223], v228 offset:33792
	s_waitcnt lgkmcnt(1)
	v_mfma_f32_16x16x32_bf16 v[12:15], v[146:149], v[216:219], v[12:15]
	v_mfma_f32_16x16x32_bf16 v[8:11], v[150:153], v[216:219], v[8:11]
	v_mfma_f32_16x16x32_bf16 v[4:7], v[154:157], v[216:219], v[4:7]
	v_mfma_f32_16x16x32_bf16 v[0:3], v[158:161], v[216:219], v[0:3]
	s_waitcnt lgkmcnt(0)
	v_mfma_f32_16x16x32_bf16 v[12:15], v[196:199], v[220:223], v[12:15]
	v_mfma_f32_16x16x32_bf16 v[8:11], v[200:203], v[220:223], v[8:11]
	v_mfma_f32_16x16x32_bf16 v[4:7], v[204:207], v[220:223], v[4:7]
	v_mfma_f32_16x16x32_bf16 v[0:3], v[208:211], v[220:223], v[0:3]
	s_branch .LBB0_278
.LBB0_279:
	s_and_b32 s75, s23, 1
	s_xor_b32 s76, s75, 1
	s_mul_i32 s76, s76, 0x10800
	s_mul_i32 s75, s75, 0x10800
	v_or_b32_e32 v128, s75, v184
	v_add_u32_e32 v226, v128, v195
	v_add_u32_e32 v227, v128, v194
	v_readfirstlane_b32 s100, v183
	s_add_i32 s100, s100, s76
	s_branch .Lgk_upproj_body

; #define WAIT_V0() asm volatile("s_waitcnt vmcnt(0)" ::: "memory")
; #define SBAR() __builtin_amdgcn_sched_barrier(0)
;     ...
;   for (int t = 0; t < nt; ++t) {
;     const int cur = t & 1;
;     if (t + 1 < nt) GLDS_STAGE(cur ^ 1, t + 1);
; #pragma unroll
;     for (int ks = 0; ks < KS; ++ks) {
;       bf16x8 At[8], Bf[NB];
; #pragma unroll
;       for (int m = 0; m < 8; ++m) At[m] = *(const bf16x8*)(SA(cur) + lds_byte<KS>(wr * 128 + m * 16 + fr, ks * 32 + fq * 8));
; #pragma unroll
;       for (int n = 0; n < NB; ++n) Bf[n] = *(const bf16x8*)(SB(cur) + lds_byte<KS>(wc * (16 * NB) + n * 16 + fr, ks * 32 + fq * 8));
; #pragma unroll
;       for (int m = 0; m < 8; ++m)
; #pragma unroll
;         for (int n = 0; n < NB; ++n) acc[m][n] = __builtin_amdgcn_mfma_f32_16x16x32_bf16(Bf[n], At[m], acc[m][n], 0, 0, 0);
;       if (xmma) {
;         const bf16x8 Ax = *(const bf16x8*)(SA(cur) + lds_byte<KS>(256 + fr, ks * 32 + fq * 8));
; #pragma unroll
;         for (int n = 0; n < NB; ++n) accx[n] = __builtin_amdgcn_mfma_f32_16x16x32_bf16(Bf[n], Ax, accx[n], 0, 0, 0);
;       }
;       SBAR();
;     }
;     WAIT_V0(); __syncthreads();
.LBB0_1294:
	s_or_b64 exec, exec, s[20:21]
	s_waitcnt vmcnt(0)
	s_add_u32 s64, s64, 0x80
	s_addc_u32 s65, s65, 0
	s_add_i32 s15, s15, 1
	s_and_b32 s22, s15, 1
	s_xor_b32 s23, s22, 1
	s_mul_i32 s23, s23, 0x10800
	s_mul_i32 s22, s22, 0x10800
	v_or_b32_e32 v195, s22, v182
	v_add_u32_e32 v226, v195, v194
	v_add_u32_e32 v227, v195, v193
	v_readfirstlane_b32 s100, v183
	s_add_i32 s100, s100, s23
	s_cmpk_lg_i32 s64, 0x780
	s_waitcnt vmcnt(0)
	s_barrier
	s_cbranch_scc0 .LBB0_1301
.Lgk_gates_body:
	ds_read_b128 v[146:149], v226 offset:34816
	ds_read_b128 v[212:215], v227
	ds_read_b128 v[150:153], v226 offset:36864
	ds_read_b128 v[154:157], v226 offset:38912
	ds_read_b128 v[158:161], v226 offset:40960
	ds_read_b128 v[216:219], v227 offset:2048
	s_mov_b32 m0, s100
	v_lshl_add_u64 v[224:225], v[162:163], 0, s[64:65]
	global_load_lds_dwordx4 v[224:225], off
	s_add_i32 m0, s100, 0x8800
	v_lshl_add_u64 v[224:225], v[170:171], 0, s[64:65]
	global_load_lds_dwordx4 v[224:225], off
	s_waitcnt lgkmcnt(1)
	v_mfma_f32_16x16x32_bf16 v[142:145], v[146:149], v[212:215], v[142:145]
	v_mfma_f32_16x16x32_bf16 v[138:141], v[150:153], v[212:215], v[138:141]
	v_mfma_f32_16x16x32_bf16 v[134:137], v[154:157], v[212:215], v[134:137]
	v_mfma_f32_16x16x32_bf16 v[130:133], v[158:161], v[212:215], v[130:133]
	ds_read_b128 v[220:223], v227 offset:4096
	s_add_i32 m0, s100, 0x2000
	v_lshl_add_u64 v[224:225], v[164:165], 0, s[64:65]
	global_load_lds_dwordx4 v[224:225], off
	s_waitcnt lgkmcnt(1)
	v_mfma_f32_16x16x32_bf16 v[124:127], v[146:149], v[216:219], v[124:127]
	v_mfma_f32_16x16x32_bf16 v[120:123], v[150:153], v[216:219], v[120:123]
	v_mfma_f32_16x16x32_bf16 v[116:119], v[154:157], v[216:219], v[116:119]
	v_mfma_f32_16x16x32_bf16 v[112:115], v[158:161], v[216:219], v[112:115]
	ds_read_b128 v[212:215], v227 offset:6144
	s_add_i32 m0, s100, 0xa800
	v_lshl_add_u64 v[224:225], v[172:173], 0, s[64:65]
	global_load_lds_dwordx4 v[224:225], off
	s_waitcnt lgkmcnt(1)
	v_mfma_f32_16x16x32_bf16 v[108:111], v[146:149], v[220:223], v[108:111]
	v_mfma_f32_16x16x32_bf16 v[104:107], v[150:153], v[220:223], v[104:107]
	v_mfma_f32_16x16x32_bf16 v[100:103], v[154:157], v[220:223], v[100:103]
	v_mfma_f32_16x16x32_bf16 v[96:99], v[158:161], v[220:223], v[96:99]
	ds_read_b128 v[216:219], v227 offset:8192
	s_add_i32 m0, s100, 0x4000
	v_lshl_add_u64 v[224:225], v[166:167], 0, s[64:65]
	global_load_lds_dwordx4 v[224:225], off
	s_waitcnt lgkmcnt(1)
	v_mfma_f32_16x16x32_bf16 v[92:95], v[146:149], v[212:215], v[92:95]
	v_mfma_f32_16x16x32_bf16 v[88:91], v[150:153], v[212:215], v[88:91]
	v_mfma_f32_16x16x32_bf16 v[84:87], v[154:157], v[212:215], v[84:87]
	v_mfma_f32_16x16x32_bf16 v[80:83], v[158:161], v[212:215], v[80:83]
	ds_read_b128 v[220:223], v227 offset:10240
	s_add_i32 m0, s100, 0xc800
	v_lshl_add_u64 v[224:225], v[174:175], 0, s[64:65]
	global_load_lds_dwordx4 v[224:225], off
	s_waitcnt lgkmcnt(1)
	v_mfma_f32_16x16x32_bf16 v[76:79], v[146:149], v[216:219], v[76:79]
	v_mfma_f32_16x16x32_bf16 v[72:75], v[150:153], v[216:219], v[72:75]
	v_mfma_f32_16x16x32_bf16 v[68:71], v[154:157], v[216:219], v[68:71]
	v_mfma_f32_16x16x32_bf16 v[64:67], v[158:161], v[216:219], v[64:67]
	ds_read_b128 v[196:199], v226 offset:35840
	ds_read_b128 v[212:215], v227 offset:12288
	s_add_i32 m0, s100, 0x6000
	v_lshl_add_u64 v[224:225], v[168:169], 0, s[64:65]
	global_load_lds_dwordx4 v[224:225], off
	s_waitcnt lgkmcnt(2)
	v_mfma_f32_16x16x32_bf16 v[60:63], v[146:149], v[220:223], v[60:63]
	v_mfma_f32_16x16x32_bf16 v[56:59], v[150:153], v[220:223], v[56:59]
	v_mfma_f32_16x16x32_bf16 v[52:55], v[154:157], v[220:223], v[52:55]
	v_mfma_f32_16x16x32_bf16 v[48:51], v[158:161], v[220:223], v[48:51]
	ds_read_b128 v[200:203], v226 offset:37888
	ds_read_b128 v[216:219], v227 offset:14336
	s_add_i32 m0, s100, 0xe800
	v_lshl_add_u64 v[224:225], v[176:177], 0, s[64:65]
	global_load_lds_dwordx4 v[224:225], off
	s_waitcnt lgkmcnt(2)
	v_mfma_f32_16x16x32_bf16 v[44:47], v[146:149], v[212:215], v[44:47]
	v_mfma_f32_16x16x32_bf16 v[40:43], v[150:153], v[212:215], v[40:43]
	v_mfma_f32_16x16x32_bf16 v[36:39], v[154:157], v[212:215], v[36:39]
	v_mfma_f32_16x16x32_bf16 v[32:35], v[158:161], v[212:215], v[32:35]
	ds_read_b128 v[204:207], v226 offset:39936
	ds_read_b128 v[220:223], v227 offset:1024
	s_and_saveexec_b64 s[20:21], s[18:19]
	s_cbranch_execz .Lgk_gates_xl
	v_readfirstlane_b32 s101, v192
	s_add_i32 s101, s101, s23
	s_add_i32 m0, s101, 0x8000
	v_lshl_add_u64 v[224:225], v[178:179], 0, s[64:65]
	global_load_lds_dwordx4 v[224:225], off
; #define WAIT_V0() asm volatile("s_waitcnt vmcnt(0)" ::: "memory")
; #define SBAR() __builtin_amdgcn_sched_barrier(0)
;     ...
;   for (int t = 0; t < nt; ++t) {
;     const int cur = t & 1;
;     if (t + 1 < nt) GLDS_STAGE(cur ^ 1, t + 1);
; #pragma unroll
;     for (int ks = 0; ks < KS; ++ks) {
;       bf16x8 At[8], Bf[NB];
; #pragma unroll
;       for (int m = 0; m < 8; ++m) At[m] = *(const bf16x8*)(SA(cur) + lds_byte<KS>(wr * 128 + m * 16 + fr, ks * 32 + fq * 8));
; #pragma unroll
;       for (int n = 0; n < NB; ++n) Bf[n] = *(const bf16x8*)(SB(cur) + lds_byte<KS>(wc * (16 * NB) + n * 16 + fr, ks * 32 + fq * 8));
; #pragma unroll
;       for (int m = 0; m < 8; ++m)
; #pragma unroll
;         for (int n = 0; n < NB; ++n) acc[m][n] = __builtin_amdgcn_mfma_f32_16x16x32_bf16(Bf[n], At[m], acc[m][n], 0, 0, 0);
;       if (xmma) {
;         const bf16x8 Ax = *(const bf16x8*)(SA(cur) + lds_byte<KS>(256 + fr, ks * 32 + fq * 8));
; #pragma unroll
;         for (int n = 0; n < NB; ++n) accx[n] = __builtin_amdgcn_mfma_f32_16x16x32_bf16(Bf[n], Ax, accx[n], 0, 0, 0);
;       }
;       SBAR();
;     }
;     WAIT_V0(); __syncthreads();
.Lgk_gates_xl:
	s_or_b64 exec, exec, s[20:21]
	s_waitcnt lgkmcnt(2)
	v_mfma_f32_16x16x32_bf16 v[28:31], v[146:149], v[216:219], v[28:31]
	v_mfma_f32_16x16x32_bf16 v[24:27], v[150:153], v[216:219], v[24:27]
	v_mfma_f32_16x16x32_bf16 v[20:23], v[154:157], v[216:219], v[20:23]
	v_mfma_f32_16x16x32_bf16 v[16:19], v[158:161], v[216:219], v[16:19]
	ds_read_b128 v[208:211], v226 offset:41984
	ds_read_b128 v[212:215], v227 offset:3072
	s_waitcnt lgkmcnt(1)
	v_mfma_f32_16x16x32_bf16 v[142:145], v[196:199], v[220:223], v[142:145]
	v_mfma_f32_16x16x32_bf16 v[138:141], v[200:203], v[220:223], v[138:141]
	v_mfma_f32_16x16x32_bf16 v[134:137], v[204:207], v[220:223], v[134:137]
	v_mfma_f32_16x16x32_bf16 v[130:133], v[208:211], v[220:223], v[130:133]
	ds_read_b128 v[216:219], v227 offset:5120
	s_waitcnt lgkmcnt(1)
	v_mfma_f32_16x16x32_bf16 v[124:127], v[196:199], v[212:215], v[124:127]
	v_mfma_f32_16x16x32_bf16 v[120:123], v[200:203], v[212:215], v[120:123]
	v_mfma_f32_16x16x32_bf16 v[116:119], v[204:207], v[212:215], v[116:119]
	v_mfma_f32_16x16x32_bf16 v[112:115], v[208:211], v[212:215], v[112:115]
	ds_read_b128 v[220:223], v227 offset:7168
	s_waitcnt lgkmcnt(1)
	v_mfma_f32_16x16x32_bf16 v[108:111], v[196:199], v[216:219], v[108:111]
	v_mfma_f32_16x16x32_bf16 v[104:107], v[200:203], v[216:219], v[104:107]
	v_mfma_f32_16x16x32_bf16 v[100:103], v[204:207], v[216:219], v[100:103]
	v_mfma_f32_16x16x32_bf16 v[96:99], v[208:211], v[216:219], v[96:99]
	ds_read_b128 v[212:215], v227 offset:9216
	s_waitcnt lgkmcnt(1)
	v_mfma_f32_16x16x32_bf16 v[92:95], v[196:199], v[220:223], v[92:95]
	v_mfma_f32_16x16x32_bf16 v[88:91], v[200:203], v[220:223], v[88:91]
	v_mfma_f32_16x16x32_bf16 v[84:87], v[204:207], v[220:223], v[84:87]
	v_mfma_f32_16x16x32_bf16 v[80:83], v[208:211], v[220:223], v[80:83]
	ds_read_b128 v[216:219], v227 offset:11264
	s_waitcnt lgkmcnt(1)
	v_mfma_f32_16x16x32_bf16 v[76:79], v[196:199], v[212:215], v[76:79]
	v_mfma_f32_16x16x32_bf16 v[72:75], v[200:203], v[212:215], v[72:75]
	v_mfma_f32_16x16x32_bf16 v[68:71], v[204:207], v[212:215], v[68:71]
	v_mfma_f32_16x16x32_bf16 v[64:67], v[208:211], v[212:215], v[64:67]
	ds_read_b128 v[220:223], v227 offset:13312
	s_waitcnt lgkmcnt(1)
	v_mfma_f32_16x16x32_bf16 v[60:63], v[196:199], v[216:219], v[60:63]
	v_mfma_f32_16x16x32_bf16 v[56:59], v[200:203], v[216:219], v[56:59]
	v_mfma_f32_16x16x32_bf16 v[52:55], v[204:207], v[216:219], v[52:55]
	v_mfma_f32_16x16x32_bf16 v[48:51], v[208:211], v[216:219], v[48:51]
	ds_read_b128 v[212:215], v227 offset:15360
	s_waitcnt lgkmcnt(1)
	v_mfma_f32_16x16x32_bf16 v[44:47], v[196:199], v[220:223], v[44:47]
	v_mfma_f32_16x16x32_bf16 v[40:43], v[200:203], v[220:223], v[40:43]
	v_mfma_f32_16x16x32_bf16 v[36:39], v[204:207], v[220:223], v[36:39]
	v_mfma_f32_16x16x32_bf16 v[32:35], v[208:211], v[220:223], v[32:35]
	s_waitcnt lgkmcnt(0)
	v_mfma_f32_16x16x32_bf16 v[28:31], v[196:199], v[212:215], v[28:31]
	v_mfma_f32_16x16x32_bf16 v[24:27], v[200:203], v[212:215], v[24:27]
	v_mfma_f32_16x16x32_bf16 v[20:23], v[204:207], v[212:215], v[20:23]
	v_mfma_f32_16x16x32_bf16 v[16:19], v[208:211], v[212:215], v[16:19]
	s_and_saveexec_b64 s[20:21], s[0:1]
	s_cbranch_execz .LBB0_1294
	v_add_u32_e32 v228, s22, v182
	ds_read_b128 v[216:219], v228 offset:32768
	ds_read_b128 v[220:223], v228 offset:33792
	s_waitcnt lgkmcnt(1)
	v_mfma_f32_16x16x32_bf16 v[12:15], v[146:149], v[216:219], v[12:15]
	v_mfma_f32_16x16x32_bf16 v[8:11], v[150:153], v[216:219], v[8:11]
	v_mfma_f32_16x16x32_bf16 v[4:7], v[154:157], v[216:219], v[4:7]
	v_mfma_f32_16x16x32_bf16 v[0:3], v[158:161], v[216:219], v[0:3]
	s_waitcnt lgkmcnt(0)
	v_mfma_f32_16x16x32_bf16 v[12:15], v[196:199], v[220:223], v[12:15]
	v_mfma_f32_16x16x32_bf16 v[8:11], v[200:203], v[220:223], v[8:11]
	v_mfma_f32_16x16x32_bf16 v[4:7], v[204:207], v[220:223], v[4:7]
	v_mfma_f32_16x16x32_bf16 v[0:3], v[208:211], v[220:223], v[0:3]
	s_branch .LBB0_1294
.LBB0_1295:
	s_and_b32 s22, s15, 1
	s_xor_b32 s23, s22, 1
	s_mul_i32 s23, s23, 0x10800
	s_mul_i32 s22, s22, 0x10800
	v_or_b32_e32 v195, s22, v182
	v_add_u32_e32 v226, v195, v194
	v_add_u32_e32 v227, v195, v193
	v_readfirstlane_b32 s100, v183
	s_add_i32 s100, s100, s23
	s_branch .Lgk_gates_body

; #define WAIT_V0() asm volatile("s_waitcnt vmcnt(0)" ::: "memory")
; #define SBAR() __builtin_amdgcn_sched_barrier(0)
;     ...
;   for (int t = 0; t < nt; ++t) {
;     const int cur = t & 1;
;     if (t + 1 < nt) GLDS_STAGE(cur ^ 1, t + 1);
; #pragma unroll
;     for (int ks = 0; ks < KS; ++ks) {
;       bf16x8 At[8], Bf[NB];
; #pragma unroll
;       for (int m = 0; m < 8; ++m) At[m] = *(const bf16x8*)(SA(cur) + lds_byte<KS>(wr * 128 + m * 16 + fr, ks * 32 + fq * 8));
; #pragma unroll
;       for (int n = 0; n < NB; ++n) Bf[n] = *(const bf16x8*)(SB(cur) + lds_byte<KS>(wc * (16 * NB) + n * 16 + fr, ks * 32 + fq * 8));
; #pragma unroll
;       for (int m = 0; m < 8; ++m)
; #pragma unroll
;         for (int n = 0; n < NB; ++n) acc[m][n] = __builtin_amdgcn_mfma_f32_16x16x32_bf16(Bf[n], At[m], acc[m][n], 0, 0, 0);
;       if (xmma) {
;         const bf16x8 Ax = *(const bf16x8*)(SA(cur) + lds_byte<KS>(256 + fr, ks * 32 + fq * 8));
; #pragma unroll
;         for (int n = 0; n < NB; ++n) accx[n] = __builtin_amdgcn_mfma_f32_16x16x32_bf16(Bf[n], Ax, accx[n], 0, 0, 0);
;       }
;       SBAR();
;     }
;     WAIT_V0(); __syncthreads();
.LBB0_1349:
	s_or_b64 exec, exec, s[20:21]
	s_waitcnt vmcnt(0)
	s_add_u32 s70, s70, 0x80
	s_addc_u32 s71, s71, 0
	s_add_i32 s3, s3, 1
	s_and_b32 s7, s3, 1
	s_xor_b32 s22, s7, 1
	s_mul_i32 s22, s22, 0x10800
	s_mul_i32 s7, s7, 0x10800
	v_or_b32_e32 v128, s7, v191
	v_add_u32_e32 v234, v128, v203
	v_add_u32_e32 v240, v128, v202
	v_readfirstlane_b32 s100, v192
	s_add_i32 s100, s100, s22
	s_cmpk_lg_i32 s70, 0x780
	s_waitcnt vmcnt(0)
	s_barrier
	s_cbranch_scc0 .LBB0_1356
.Lgk_out_body:
	ds_read_b128 v[146:149], v234 offset:34816
	ds_read_b128 v[220:223], v240
	ds_read_b128 v[150:153], v234 offset:36864
	ds_read_b128 v[154:157], v234 offset:38912
	ds_read_b128 v[158:161], v234 offset:40960
	ds_read_b128 v[224:227], v240 offset:2048
	s_mov_b32 m0, s100
	v_lshl_add_u64 v[238:239], v[162:163], 0, s[70:71]
	global_load_lds_dwordx4 v[238:239], off
	s_add_i32 m0, s100, 0x8800
	v_lshl_add_u64 v[238:239], v[170:171], 0, s[70:71]
	global_load_lds_dwordx4 v[238:239], off
	s_waitcnt lgkmcnt(1)
	v_mfma_f32_16x16x32_bf16 v[142:145], v[146:149], v[220:223], v[142:145]
	v_mfma_f32_16x16x32_bf16 v[138:141], v[150:153], v[220:223], v[138:141]
	v_mfma_f32_16x16x32_bf16 v[134:137], v[154:157], v[220:223], v[134:137]
	v_mfma_f32_16x16x32_bf16 v[130:133], v[158:161], v[220:223], v[130:133]
	ds_read_b128 v[228:231], v240 offset:4096
	s_add_i32 m0, s100, 0x2000
	v_lshl_add_u64 v[238:239], v[164:165], 0, s[70:71]
	global_load_lds_dwordx4 v[238:239], off
	s_waitcnt lgkmcnt(1)
	v_mfma_f32_16x16x32_bf16 v[124:127], v[146:149], v[224:227], v[124:127]
	v_mfma_f32_16x16x32_bf16 v[120:123], v[150:153], v[224:227], v[120:123]
	v_mfma_f32_16x16x32_bf16 v[116:119], v[154:157], v[224:227], v[116:119]
	v_mfma_f32_16x16x32_bf16 v[112:115], v[158:161], v[224:227], v[112:115]
	ds_read_b128 v[220:223], v240 offset:6144
	s_add_i32 m0, s100, 0xa800
	v_lshl_add_u64 v[238:239], v[172:173], 0, s[70:71]
	global_load_lds_dwordx4 v[238:239], off
	s_waitcnt lgkmcnt(1)
	v_mfma_f32_16x16x32_bf16 v[108:111], v[146:149], v[228:231], v[108:111]
	v_mfma_f32_16x16x32_bf16 v[104:107], v[150:153], v[228:231], v[104:107]
	v_mfma_f32_16x16x32_bf16 v[100:103], v[154:157], v[228:231], v[100:103]
	v_mfma_f32_16x16x32_bf16 v[96:99], v[158:161], v[228:231], v[96:99]
	ds_read_b128 v[224:227], v240 offset:8192
	s_add_i32 m0, s100, 0x4000
	v_lshl_add_u64 v[238:239], v[166:167], 0, s[70:71]
	global_load_lds_dwordx4 v[238:239], off
	s_waitcnt lgkmcnt(1)
	v_mfma_f32_16x16x32_bf16 v[92:95], v[146:149], v[220:223], v[92:95]
	v_mfma_f32_16x16x32_bf16 v[88:91], v[150:153], v[220:223], v[88:91]
	v_mfma_f32_16x16x32_bf16 v[84:87], v[154:157], v[220:223], v[84:87]
	v_mfma_f32_16x16x32_bf16 v[80:83], v[158:161], v[220:223], v[80:83]
	ds_read_b128 v[228:231], v240 offset:10240
	s_add_i32 m0, s100, 0xc800
	v_lshl_add_u64 v[238:239], v[174:175], 0, s[70:71]
	global_load_lds_dwordx4 v[238:239], off
	s_waitcnt lgkmcnt(1)
	v_mfma_f32_16x16x32_bf16 v[76:79], v[146:149], v[224:227], v[76:79]
	v_mfma_f32_16x16x32_bf16 v[72:75], v[150:153], v[224:227], v[72:75]
	v_mfma_f32_16x16x32_bf16 v[68:71], v[154:157], v[224:227], v[68:71]
	v_mfma_f32_16x16x32_bf16 v[64:67], v[158:161], v[224:227], v[64:67]
	ds_read_b128 v[204:207], v234 offset:35840
	ds_read_b128 v[220:223], v240 offset:12288
	s_add_i32 m0, s100, 0x6000
	v_lshl_add_u64 v[238:239], v[168:169], 0, s[70:71]
	global_load_lds_dwordx4 v[238:239], off
	s_waitcnt lgkmcnt(2)
	v_mfma_f32_16x16x32_bf16 v[60:63], v[146:149], v[228:231], v[60:63]
	v_mfma_f32_16x16x32_bf16 v[56:59], v[150:153], v[228:231], v[56:59]
	v_mfma_f32_16x16x32_bf16 v[52:55], v[154:157], v[228:231], v[52:55]
	v_mfma_f32_16x16x32_bf16 v[48:51], v[158:161], v[228:231], v[48:51]
	ds_read_b128 v[208:211], v234 offset:37888
	ds_read_b128 v[224:227], v240 offset:14336
	s_add_i32 m0, s100, 0xe800
	v_lshl_add_u64 v[238:239], v[176:177], 0, s[70:71]
	global_load_lds_dwordx4 v[238:239], off
	s_waitcnt lgkmcnt(2)
	v_mfma_f32_16x16x32_bf16 v[44:47], v[146:149], v[220:223], v[44:47]
	v_mfma_f32_16x16x32_bf16 v[40:43], v[150:153], v[220:223], v[40:43]
	v_mfma_f32_16x16x32_bf16 v[36:39], v[154:157], v[220:223], v[36:39]
	v_mfma_f32_16x16x32_bf16 v[32:35], v[158:161], v[220:223], v[32:35]
	ds_read_b128 v[212:215], v234 offset:39936
	ds_read_b128 v[228:231], v240 offset:1024
	s_and_saveexec_b64 s[20:21], s[68:69]
	s_cbranch_execz .Lgk_out_xl
	v_readfirstlane_b32 s101, v201
	s_add_i32 s101, s101, s22
	s_add_i32 m0, s101, 0x8000
	v_lshl_add_u64 v[238:239], v[178:179], 0, s[70:71]
	global_load_lds_dwordx4 v[238:239], off
; #define WAIT_V0() asm volatile("s_waitcnt vmcnt(0)" ::: "memory")
; #define SBAR() __builtin_amdgcn_sched_barrier(0)
;     ...
;   for (int t = 0; t < nt; ++t) {
;     const int cur = t & 1;
;     if (t + 1 < nt) GLDS_STAGE(cur ^ 1, t + 1);
; #pragma unroll
;     for (int ks = 0; ks < KS; ++ks) {
;       bf16x8 At[8], Bf[NB];
; #pragma unroll
;       for (int m = 0; m < 8; ++m) At[m] = *(const bf16x8*)(SA(cur) + lds_byte<KS>(wr * 128 + m * 16 + fr, ks * 32 + fq * 8));
; #pragma unroll
;       for (int n = 0; n < NB; ++n) Bf[n] = *(const bf16x8*)(SB(cur) + lds_byte<KS>(wc * (16 * NB) + n * 16 + fr, ks * 32 + fq * 8));
; #pragma unroll
;       for (int m = 0; m < 8; ++m)
; #pragma unroll
;         for (int n = 0; n < NB; ++n) acc[m][n] = __builtin_amdgcn_mfma_f32_16x16x32_bf16(Bf[n], At[m], acc[m][n], 0, 0, 0);
;       if (xmma) {
;         const bf16x8 Ax = *(const bf16x8*)(SA(cur) + lds_byte<KS>(256 + fr, ks * 32 + fq * 8));
; #pragma unroll
;         for (int n = 0; n < NB; ++n) accx[n] = __builtin_amdgcn_mfma_f32_16x16x32_bf16(Bf[n], Ax, accx[n], 0, 0, 0);
;       }
;       SBAR();
;     }
;     WAIT_V0(); __syncthreads();
.Lgk_out_xl:
	s_or_b64 exec, exec, s[20:21]
	s_waitcnt lgkmcnt(2)
	v_mfma_f32_16x16x32_bf16 v[28:31], v[146:149], v[224:227], v[28:31]
	v_mfma_f32_16x16x32_bf16 v[24:27], v[150:153], v[224:227], v[24:27]
	v_mfma_f32_16x16x32_bf16 v[20:23], v[154:157], v[224:227], v[20:23]
	v_mfma_f32_16x16x32_bf16 v[16:19], v[158:161], v[224:227], v[16:19]
	ds_read_b128 v[216:219], v234 offset:41984
	ds_read_b128 v[220:223], v240 offset:3072
	s_waitcnt lgkmcnt(1)
	v_mfma_f32_16x16x32_bf16 v[142:145], v[204:207], v[228:231], v[142:145]
	v_mfma_f32_16x16x32_bf16 v[138:141], v[208:211], v[228:231], v[138:141]
	v_mfma_f32_16x16x32_bf16 v[134:137], v[212:215], v[228:231], v[134:137]
	v_mfma_f32_16x16x32_bf16 v[130:133], v[216:219], v[228:231], v[130:133]
	ds_read_b128 v[224:227], v240 offset:5120
	s_waitcnt lgkmcnt(1)
	v_mfma_f32_16x16x32_bf16 v[124:127], v[204:207], v[220:223], v[124:127]
	v_mfma_f32_16x16x32_bf16 v[120:123], v[208:211], v[220:223], v[120:123]
	v_mfma_f32_16x16x32_bf16 v[116:119], v[212:215], v[220:223], v[116:119]
	v_mfma_f32_16x16x32_bf16 v[112:115], v[216:219], v[220:223], v[112:115]
	ds_read_b128 v[228:231], v240 offset:7168
	s_waitcnt lgkmcnt(1)
	v_mfma_f32_16x16x32_bf16 v[108:111], v[204:207], v[224:227], v[108:111]
	v_mfma_f32_16x16x32_bf16 v[104:107], v[208:211], v[224:227], v[104:107]
	v_mfma_f32_16x16x32_bf16 v[100:103], v[212:215], v[224:227], v[100:103]
	v_mfma_f32_16x16x32_bf16 v[96:99], v[216:219], v[224:227], v[96:99]
	ds_read_b128 v[220:223], v240 offset:9216
	s_waitcnt lgkmcnt(1)
	v_mfma_f32_16x16x32_bf16 v[92:95], v[204:207], v[228:231], v[92:95]
	v_mfma_f32_16x16x32_bf16 v[88:91], v[208:211], v[228:231], v[88:91]
	v_mfma_f32_16x16x32_bf16 v[84:87], v[212:215], v[228:231], v[84:87]
	v_mfma_f32_16x16x32_bf16 v[80:83], v[216:219], v[228:231], v[80:83]
	ds_read_b128 v[224:227], v240 offset:11264
	s_waitcnt lgkmcnt(1)
	v_mfma_f32_16x16x32_bf16 v[76:79], v[204:207], v[220:223], v[76:79]
	v_mfma_f32_16x16x32_bf16 v[72:75], v[208:211], v[220:223], v[72:75]
	v_mfma_f32_16x16x32_bf16 v[68:71], v[212:215], v[220:223], v[68:71]
	v_mfma_f32_16x16x32_bf16 v[64:67], v[216:219], v[220:223], v[64:67]
	ds_read_b128 v[228:231], v240 offset:13312
	s_waitcnt lgkmcnt(1)
	v_mfma_f32_16x16x32_bf16 v[60:63], v[204:207], v[224:227], v[60:63]
	v_mfma_f32_16x16x32_bf16 v[56:59], v[208:211], v[224:227], v[56:59]
	v_mfma_f32_16x16x32_bf16 v[52:55], v[212:215], v[224:227], v[52:55]
	v_mfma_f32_16x16x32_bf16 v[48:51], v[216:219], v[224:227], v[48:51]
	ds_read_b128 v[220:223], v240 offset:15360
	s_waitcnt lgkmcnt(1)
	v_mfma_f32_16x16x32_bf16 v[44:47], v[204:207], v[228:231], v[44:47]
	v_mfma_f32_16x16x32_bf16 v[40:43], v[208:211], v[228:231], v[40:43]
	v_mfma_f32_16x16x32_bf16 v[36:39], v[212:215], v[228:231], v[36:39]
	v_mfma_f32_16x16x32_bf16 v[32:35], v[216:219], v[228:231], v[32:35]
	s_waitcnt lgkmcnt(0)
	v_mfma_f32_16x16x32_bf16 v[28:31], v[204:207], v[220:223], v[28:31]
	v_mfma_f32_16x16x32_bf16 v[24:27], v[208:211], v[220:223], v[24:27]
	v_mfma_f32_16x16x32_bf16 v[20:23], v[212:215], v[220:223], v[20:23]
	v_mfma_f32_16x16x32_bf16 v[16:19], v[216:219], v[220:223], v[16:19]
	s_and_saveexec_b64 s[20:21], s[4:5]
	s_cbranch_execz .LBB0_1349
	v_add_u32_e32 v241, s7, v191
	ds_read_b128 v[224:227], v241 offset:32768
	ds_read_b128 v[228:231], v241 offset:33792
	s_waitcnt lgkmcnt(1)
	v_mfma_f32_16x16x32_bf16 v[12:15], v[146:149], v[224:227], v[12:15]
	v_mfma_f32_16x16x32_bf16 v[8:11], v[150:153], v[224:227], v[8:11]
	v_mfma_f32_16x16x32_bf16 v[4:7], v[154:157], v[224:227], v[4:7]
	v_mfma_f32_16x16x32_bf16 v[0:3], v[158:161], v[224:227], v[0:3]
	s_waitcnt lgkmcnt(0)
	v_mfma_f32_16x16x32_bf16 v[12:15], v[204:207], v[228:231], v[12:15]
	v_mfma_f32_16x16x32_bf16 v[8:11], v[208:211], v[228:231], v[8:11]
	v_mfma_f32_16x16x32_bf16 v[4:7], v[212:215], v[228:231], v[4:7]
	v_mfma_f32_16x16x32_bf16 v[0:3], v[216:219], v[228:231], v[0:3]
	s_branch .LBB0_1349
.LBB0_1350:
	s_and_b32 s7, s3, 1
	s_xor_b32 s22, s7, 1
	s_mul_i32 s22, s22, 0x10800
	s_mul_i32 s7, s7, 0x10800
	v_or_b32_e32 v128, s7, v191
	v_add_u32_e32 v234, v128, v203
	v_add_u32_e32 v240, v128, v202
	v_readfirstlane_b32 s100, v192
	s_add_i32 s100, s100, s22
	s_branch .Lgk_out_body

; #define WAIT_V0() asm volatile("s_waitcnt vmcnt(0)" ::: "memory")
; #define SBAR() __builtin_amdgcn_sched_barrier(0)
;     ...
;   for (int t = 0; t < nt; ++t) {
;     const int cur = t & 1;
;     if (t + 1 < nt) GLDS_STAGE(cur ^ 1, t + 1);
; #pragma unroll
;     for (int ks = 0; ks < KS; ++ks) {
;       bf16x8 At[8], Bf[NB];
; #pragma unroll
;       for (int m = 0; m < 8; ++m) At[m] = *(const bf16x8*)(SA(cur) + lds_byte<KS>(wr * 128 + m * 16 + fr, ks * 32 + fq * 8));
; #pragma unroll
;       for (int n = 0; n < NB; ++n) Bf[n] = *(const bf16x8*)(SB(cur) + lds_byte<KS>(wc * (16 * NB) + n * 16 + fr, ks * 32 + fq * 8));
; #pragma unroll
;       for (int m = 0; m < 8; ++m)
; #pragma unroll
;         for (int n = 0; n < NB; ++n) acc[m][n] = __builtin_amdgcn_mfma_f32_16x16x32_bf16(Bf[n], At[m], acc[m][n], 0, 0, 0);
;       if (xmma) {
;         const bf16x8 Ax = *(const bf16x8*)(SA(cur) + lds_byte<KS>(256 + fr, ks * 32 + fq * 8));
; #pragma unroll
;         for (int n = 0; n < NB; ++n) accx[n] = __builtin_amdgcn_mfma_f32_16x16x32_bf16(Bf[n], Ax, accx[n], 0, 0, 0);
;       }
;       SBAR();
;     }
;     WAIT_V0(); __syncthreads();
.LBB0_1743:
	s_or_b64 exec, exec, s[20:21]
	s_waitcnt vmcnt(0)
	s_add_u32 s66, s66, 0x80
	s_addc_u32 s67, s67, 0
	s_add_i32 s3, s3, 1
	s_and_b32 s5, s3, 1
	s_xor_b32 s17, s5, 1
	s_mul_i32 s17, s17, 0x10800
	s_mul_i32 s5, s5, 0x10800
	v_or_b32_e32 v128, s5, v191
	v_add_u32_e32 v234, v128, v203
	v_add_u32_e32 v240, v128, v202
	v_readfirstlane_b32 s100, v192
	s_add_i32 s100, s100, s17
	s_cmpk_lg_i32 s66, 0x1f80
	s_waitcnt vmcnt(0)
	s_barrier
	s_cbranch_scc0 .LBB0_1750
.Lgk_down_body:
	ds_read_b128 v[146:149], v234 offset:34816
	ds_read_b128 v[220:223], v240
	ds_read_b128 v[150:153], v234 offset:36864
	ds_read_b128 v[154:157], v234 offset:38912
	ds_read_b128 v[158:161], v234 offset:40960
	ds_read_b128 v[224:227], v240 offset:2048
	s_mov_b32 m0, s100
	v_lshl_add_u64 v[238:239], v[162:163], 0, s[66:67]
	global_load_lds_dwordx4 v[238:239], off
	s_add_i32 m0, s100, 0x8800
	v_lshl_add_u64 v[238:239], v[170:171], 0, s[66:67]
	global_load_lds_dwordx4 v[238:239], off
	s_waitcnt lgkmcnt(1)
	v_mfma_f32_16x16x32_bf16 v[142:145], v[146:149], v[220:223], v[142:145]
	v_mfma_f32_16x16x32_bf16 v[138:141], v[150:153], v[220:223], v[138:141]
	v_mfma_f32_16x16x32_bf16 v[134:137], v[154:157], v[220:223], v[134:137]
	v_mfma_f32_16x16x32_bf16 v[130:133], v[158:161], v[220:223], v[130:133]
	ds_read_b128 v[228:231], v240 offset:4096
	s_add_i32 m0, s100, 0x2000
	v_lshl_add_u64 v[238:239], v[164:165], 0, s[66:67]
	global_load_lds_dwordx4 v[238:239], off
	s_waitcnt lgkmcnt(1)
	v_mfma_f32_16x16x32_bf16 v[124:127], v[146:149], v[224:227], v[124:127]
	v_mfma_f32_16x16x32_bf16 v[120:123], v[150:153], v[224:227], v[120:123]
	v_mfma_f32_16x16x32_bf16 v[116:119], v[154:157], v[224:227], v[116:119]
	v_mfma_f32_16x16x32_bf16 v[112:115], v[158:161], v[224:227], v[112:115]
	ds_read_b128 v[220:223], v240 offset:6144
	s_add_i32 m0, s100, 0xa800
	v_lshl_add_u64 v[238:239], v[172:173], 0, s[66:67]
	global_load_lds_dwordx4 v[238:239], off
	s_waitcnt lgkmcnt(1)
	v_mfma_f32_16x16x32_bf16 v[108:111], v[146:149], v[228:231], v[108:111]
	v_mfma_f32_16x16x32_bf16 v[104:107], v[150:153], v[228:231], v[104:107]
	v_mfma_f32_16x16x32_bf16 v[100:103], v[154:157], v[228:231], v[100:103]
	v_mfma_f32_16x16x32_bf16 v[96:99], v[158:161], v[228:231], v[96:99]
	ds_read_b128 v[224:227], v240 offset:8192
	s_add_i32 m0, s100, 0x4000
	v_lshl_add_u64 v[238:239], v[166:167], 0, s[66:67]
	global_load_lds_dwordx4 v[238:239], off
	s_waitcnt lgkmcnt(1)
	v_mfma_f32_16x16x32_bf16 v[92:95], v[146:149], v[220:223], v[92:95]
	v_mfma_f32_16x16x32_bf16 v[88:91], v[150:153], v[220:223], v[88:91]
	v_mfma_f32_16x16x32_bf16 v[84:87], v[154:157], v[220:223], v[84:87]
	v_mfma_f32_16x16x32_bf16 v[80:83], v[158:161], v[220:223], v[80:83]
	ds_read_b128 v[228:231], v240 offset:10240
	s_add_i32 m0, s100, 0xc800
	v_lshl_add_u64 v[238:239], v[174:175], 0, s[66:67]
	global_load_lds_dwordx4 v[238:239], off
	s_waitcnt lgkmcnt(1)
	v_mfma_f32_16x16x32_bf16 v[76:79], v[146:149], v[224:227], v[76:79]
	v_mfma_f32_16x16x32_bf16 v[72:75], v[150:153], v[224:227], v[72:75]
	v_mfma_f32_16x16x32_bf16 v[68:71], v[154:157], v[224:227], v[68:71]
	v_mfma_f32_16x16x32_bf16 v[64:67], v[158:161], v[224:227], v[64:67]
	ds_read_b128 v[204:207], v234 offset:35840
	ds_read_b128 v[220:223], v240 offset:12288
	s_add_i32 m0, s100, 0x6000
	v_lshl_add_u64 v[238:239], v[168:169], 0, s[66:67]
	global_load_lds_dwordx4 v[238:239], off
	s_waitcnt lgkmcnt(2)
	v_mfma_f32_16x16x32_bf16 v[60:63], v[146:149], v[228:231], v[60:63]
	v_mfma_f32_16x16x32_bf16 v[56:59], v[150:153], v[228:231], v[56:59]
	v_mfma_f32_16x16x32_bf16 v[52:55], v[154:157], v[228:231], v[52:55]
	v_mfma_f32_16x16x32_bf16 v[48:51], v[158:161], v[228:231], v[48:51]
	ds_read_b128 v[208:211], v234 offset:37888
	ds_read_b128 v[224:227], v240 offset:14336
	s_add_i32 m0, s100, 0xe800
	v_lshl_add_u64 v[238:239], v[176:177], 0, s[66:67]
	global_load_lds_dwordx4 v[238:239], off
	s_waitcnt lgkmcnt(2)
	v_mfma_f32_16x16x32_bf16 v[44:47], v[146:149], v[220:223], v[44:47]
	v_mfma_f32_16x16x32_bf16 v[40:43], v[150:153], v[220:223], v[40:43]
	v_mfma_f32_16x16x32_bf16 v[36:39], v[154:157], v[220:223], v[36:39]
	v_mfma_f32_16x16x32_bf16 v[32:35], v[158:161], v[220:223], v[32:35]
	ds_read_b128 v[212:215], v234 offset:39936
	ds_read_b128 v[228:231], v240 offset:1024
	s_and_saveexec_b64 s[20:21], s[64:65]
	s_cbranch_execz .Lgk_down_xl
	v_readfirstlane_b32 s101, v201
	s_add_i32 s101, s101, s17
	s_add_i32 m0, s101, 0x8000
	v_lshl_add_u64 v[238:239], v[178:179], 0, s[66:67]
	global_load_lds_dwordx4 v[238:239], off
; #define WAIT_V0() asm volatile("s_waitcnt vmcnt(0)" ::: "memory")
; #define SBAR() __builtin_amdgcn_sched_barrier(0)
;     ...
;   for (int t = 0; t < nt; ++t) {
;     const int cur = t & 1;
;     if (t + 1 < nt) GLDS_STAGE(cur ^ 1, t + 1);
; #pragma unroll
;     for (int ks = 0; ks < KS; ++ks) {
;       bf16x8 At[8], Bf[NB];
; #pragma unroll
;       for (int m = 0; m < 8; ++m) At[m] = *(const bf16x8*)(SA(cur) + lds_byte<KS>(wr * 128 + m * 16 + fr, ks * 32 + fq * 8));
; #pragma unroll
;       for (int n = 0; n < NB; ++n) Bf[n] = *(const bf16x8*)(SB(cur) + lds_byte<KS>(wc * (16 * NB) + n * 16 + fr, ks * 32 + fq * 8));
; #pragma unroll
;       for (int m = 0; m < 8; ++m)
; #pragma unroll
;         for (int n = 0; n < NB; ++n) acc[m][n] = __builtin_amdgcn_mfma_f32_16x16x32_bf16(Bf[n], At[m], acc[m][n], 0, 0, 0);
;       if (xmma) {
;         const bf16x8 Ax = *(const bf16x8*)(SA(cur) + lds_byte<KS>(256 + fr, ks * 32 + fq * 8));
; #pragma unroll
;         for (int n = 0; n < NB; ++n) accx[n] = __builtin_amdgcn_mfma_f32_16x16x32_bf16(Bf[n], Ax, accx[n], 0, 0, 0);
;       }
;       SBAR();
;     }
;     WAIT_V0(); __syncthreads();
.Lgk_down_xl:
	s_or_b64 exec, exec, s[20:21]
	s_waitcnt lgkmcnt(2)
	v_mfma_f32_16x16x32_bf16 v[28:31], v[146:149], v[224:227], v[28:31]
	v_mfma_f32_16x16x32_bf16 v[24:27], v[150:153], v[224:227], v[24:27]
	v_mfma_f32_16x16x32_bf16 v[20:23], v[154:157], v[224:227], v[20:23]
	v_mfma_f32_16x16x32_bf16 v[16:19], v[158:161], v[224:227], v[16:19]
	ds_read_b128 v[216:219], v234 offset:41984
	ds_read_b128 v[220:223], v240 offset:3072
	s_waitcnt lgkmcnt(1)
	v_mfma_f32_16x16x32_bf16 v[142:145], v[204:207], v[228:231], v[142:145]
	v_mfma_f32_16x16x32_bf16 v[138:141], v[208:211], v[228:231], v[138:141]
	v_mfma_f32_16x16x32_bf16 v[134:137], v[212:215], v[228:231], v[134:137]
	v_mfma_f32_16x16x32_bf16 v[130:133], v[216:219], v[228:231], v[130:133]
	ds_read_b128 v[224:227], v240 offset:5120
	s_waitcnt lgkmcnt(1)
	v_mfma_f32_16x16x32_bf16 v[124:127], v[204:207], v[220:223], v[124:127]
	v_mfma_f32_16x16x32_bf16 v[120:123], v[208:211], v[220:223], v[120:123]
	v_mfma_f32_16x16x32_bf16 v[116:119], v[212:215], v[220:223], v[116:119]
	v_mfma_f32_16x16x32_bf16 v[112:115], v[216:219], v[220:223], v[112:115]
	ds_read_b128 v[228:231], v240 offset:7168
	s_waitcnt lgkmcnt(1)
	v_mfma_f32_16x16x32_bf16 v[108:111], v[204:207], v[224:227], v[108:111]
	v_mfma_f32_16x16x32_bf16 v[104:107], v[208:211], v[224:227], v[104:107]
	v_mfma_f32_16x16x32_bf16 v[100:103], v[212:215], v[224:227], v[100:103]
	v_mfma_f32_16x16x32_bf16 v[96:99], v[216:219], v[224:227], v[96:99]
	ds_read_b128 v[220:223], v240 offset:9216
	s_waitcnt lgkmcnt(1)
	v_mfma_f32_16x16x32_bf16 v[92:95], v[204:207], v[228:231], v[92:95]
	v_mfma_f32_16x16x32_bf16 v[88:91], v[208:211], v[228:231], v[88:91]
	v_mfma_f32_16x16x32_bf16 v[84:87], v[212:215], v[228:231], v[84:87]
	v_mfma_f32_16x16x32_bf16 v[80:83], v[216:219], v[228:231], v[80:83]
	ds_read_b128 v[224:227], v240 offset:11264
	s_waitcnt lgkmcnt(1)
	v_mfma_f32_16x16x32_bf16 v[76:79], v[204:207], v[220:223], v[76:79]
	v_mfma_f32_16x16x32_bf16 v[72:75], v[208:211], v[220:223], v[72:75]
	v_mfma_f32_16x16x32_bf16 v[68:71], v[212:215], v[220:223], v[68:71]
	v_mfma_f32_16x16x32_bf16 v[64:67], v[216:219], v[220:223], v[64:67]
	ds_read_b128 v[228:231], v240 offset:13312
	s_waitcnt lgkmcnt(1)
	v_mfma_f32_16x16x32_bf16 v[60:63], v[204:207], v[224:227], v[60:63]
	v_mfma_f32_16x16x32_bf16 v[56:59], v[208:211], v[224:227], v[56:59]
	v_mfma_f32_16x16x32_bf16 v[52:55], v[212:215], v[224:227], v[52:55]
	v_mfma_f32_16x16x32_bf16 v[48:51], v[216:219], v[224:227], v[48:51]
	ds_read_b128 v[220:223], v240 offset:15360
	s_waitcnt lgkmcnt(1)
	v_mfma_f32_16x16x32_bf16 v[44:47], v[204:207], v[228:231], v[44:47]
	v_mfma_f32_16x16x32_bf16 v[40:43], v[208:211], v[228:231], v[40:43]
	v_mfma_f32_16x16x32_bf16 v[36:39], v[212:215], v[228:231], v[36:39]
	v_mfma_f32_16x16x32_bf16 v[32:35], v[216:219], v[228:231], v[32:35]
	s_waitcnt lgkmcnt(0)
	v_mfma_f32_16x16x32_bf16 v[28:31], v[204:207], v[220:223], v[28:31]
	v_mfma_f32_16x16x32_bf16 v[24:27], v[208:211], v[220:223], v[24:27]
	v_mfma_f32_16x16x32_bf16 v[20:23], v[212:215], v[220:223], v[20:23]
	v_mfma_f32_16x16x32_bf16 v[16:19], v[216:219], v[220:223], v[16:19]
	s_and_saveexec_b64 s[20:21], s[62:63]
	s_cbranch_execz .LBB0_1743
	v_add_u32_e32 v241, s5, v191
	ds_read_b128 v[224:227], v241 offset:32768
	ds_read_b128 v[228:231], v241 offset:33792
	s_waitcnt lgkmcnt(1)
	v_mfma_f32_16x16x32_bf16 v[12:15], v[146:149], v[224:227], v[12:15]
	v_mfma_f32_16x16x32_bf16 v[8:11], v[150:153], v[224:227], v[8:11]
	v_mfma_f32_16x16x32_bf16 v[4:7], v[154:157], v[224:227], v[4:7]
	v_mfma_f32_16x16x32_bf16 v[0:3], v[158:161], v[224:227], v[0:3]
	s_waitcnt lgkmcnt(0)
	v_mfma_f32_16x16x32_bf16 v[12:15], v[204:207], v[228:231], v[12:15]
	v_mfma_f32_16x16x32_bf16 v[8:11], v[208:211], v[228:231], v[8:11]
	v_mfma_f32_16x16x32_bf16 v[4:7], v[212:215], v[228:231], v[4:7]
	v_mfma_f32_16x16x32_bf16 v[0:3], v[216:219], v[228:231], v[0:3]
	s_branch .LBB0_1743
.LBB0_1744:
	s_and_b32 s5, s3, 1
	s_xor_b32 s17, s5, 1
	s_mul_i32 s17, s17, 0x10800
	s_mul_i32 s5, s5, 0x10800
	v_or_b32_e32 v128, s5, v191
	v_add_u32_e32 v234, v128, v203
	v_add_u32_e32 v240, v128, v202
	v_readfirstlane_b32 s100, v192
	s_add_i32 s100, s100, s17
	s_branch .Lgk_down_body
